# bar_nowb + NA/FFT mixer outputs written through (sc1)
# baseline (speedup 1.0000x reference)
.LBB0_280:
	s_waitcnt vmcnt(3)
	v_and_b32_e32 v1, 64, v158
	v_xor_b32_e32 v0, 16, v158
	v_add_u32_e32 v1, 64, v1
	v_cmp_lt_i32_e32 vcc, v0, v1
	v_xor_b32_e32 v2, 32, v158
	s_lshl_b32 s24, s27, 1
	v_cndmask_b32_e32 v0, v158, v0, vcc
	s_waitcnt vmcnt(2)
	v_lshlrev_b32_e32 v7, 2, v0
	ds_bpermute_b32 v0, v7, v102
	v_cmp_lt_i32_e32 vcc, v2, v1
	v_lshl_add_u64 v[4:5], v[88:89], 0, s[24:25]
	s_add_i32 s45, s45, s3
	v_cndmask_b32_e32 v1, v158, v2, vcc
	v_lshlrev_b32_e32 v14, 2, v1
	s_waitcnt lgkmcnt(0)
	v_add_f32_e32 v0, v102, v0
	ds_bpermute_b32 v1, v14, v0
	s_add_i32 s46, s46, 1
	s_cmpk_gt_i32 s45, 0x1ff
	s_waitcnt lgkmcnt(0)
	v_add_f32_e32 v0, v0, v1
	v_div_scale_f32 v1, s[16:17], v0, v0, 1.0
	v_rcp_f32_e32 v2, v1
	v_div_scale_f32 v3, vcc, 1.0, v0, 1.0
	v_fma_f32 v6, -v1, v2, 1.0
	v_fmac_f32_e32 v2, v6, v2
	v_mul_f32_e32 v6, v3, v2
	v_fma_f32 v8, -v1, v6, v3
	v_fmac_f32_e32 v6, v8, v2
	v_fma_f32 v1, -v1, v6, v3
	v_div_fmas_f32 v1, v1, v2, v6
	v_div_fixup_f32 v6, v1, v0, 1.0
	v_lshlrev_b64 v[0:1], 12, v[96:97]
	v_lshl_add_u64 v[8:9], v[4:5], 0, v[0:1]
	v_pk_mul_f32 v[10:11], v[6:7], v[78:79] op_sel_hi:[0,1]
	v_pk_mul_f32 v[0:1], v[6:7], v[76:77] op_sel_hi:[0,1]
	v_pk_mul_f32 v[12:13], v[6:7], v[66:67] op_sel_hi:[0,1]
	v_pk_mul_f32 v[2:3], v[6:7], v[64:65] op_sel_hi:[0,1]
	v_cvt_pk_bf16_f32 v0, v0, v1
	v_cvt_pk_bf16_f32 v2, v2, v3
	v_cvt_pk_bf16_f32 v1, v10, v11
	v_cvt_pk_bf16_f32 v3, v12, v13
	v_permlane16_swap_b32_e32 v0, v2
	s_nop 0
	v_permlane16_swap_b32_e32 v1, v3
	global_store_dwordx4 v[8:9], v[0:3], off sc1
	v_pk_mul_f32 v[10:11], v[6:7], v[74:75] op_sel_hi:[0,1]
	s_nop 0
	v_pk_mul_f32 v[0:1], v[6:7], v[72:73] op_sel_hi:[0,1]
	ds_bpermute_b32 v7, v7, v103
	v_cvt_pk_bf16_f32 v0, v0, v1
	v_cvt_pk_bf16_f32 v1, v10, v11
	s_waitcnt lgkmcnt(0)
	v_pk_mul_f32 v[12:13], v[6:7], v[70:71] op_sel_hi:[0,1]
	v_pk_mul_f32 v[2:3], v[6:7], v[68:69] op_sel_hi:[0,1]
	v_add_f32_e32 v6, v103, v7
	ds_bpermute_b32 v7, v14, v6
	v_cvt_pk_bf16_f32 v2, v2, v3
	v_cvt_pk_bf16_f32 v3, v12, v13
	s_nop 0
	v_permlane16_swap_b32_e32 v0, v2
	s_waitcnt lgkmcnt(0)
	v_add_f32_e32 v6, v6, v7
	v_div_scale_f32 v7, s[16:17], v6, v6, 1.0
	v_rcp_f32_e32 v10, v7
	v_permlane16_swap_b32_e32 v1, v3
	global_store_dwordx4 v[8:9], v[0:3], off offset:64 sc1
	s_nop 1
	v_fma_f32 v0, -v7, v10, 1.0
	v_fmac_f32_e32 v10, v0, v10
	v_div_scale_f32 v0, vcc, 1.0, v6, 1.0
	v_mul_f32_e32 v1, v0, v10
	v_fma_f32 v2, -v7, v1, v0
	v_fmac_f32_e32 v1, v2, v10
	v_fma_f32 v0, -v7, v1, v0
	v_div_fmas_f32 v0, v0, v10, v1
	v_div_fixup_f32 v6, v0, v6, 1.0
	v_lshlrev_b64 v[0:1], 12, v[94:95]
	v_lshl_add_u64 v[4:5], v[4:5], 0, v[0:1]
	v_pk_mul_f32 v[8:9], v[6:7], v[62:63] op_sel_hi:[0,1]
	v_pk_mul_f32 v[0:1], v[6:7], v[60:61] op_sel_hi:[0,1]
	v_pk_mul_f32 v[10:11], v[6:7], v[58:59] op_sel_hi:[0,1]
	v_pk_mul_f32 v[2:3], v[6:7], v[56:57] op_sel_hi:[0,1]
	v_cvt_pk_bf16_f32 v0, v0, v1
	v_cvt_pk_bf16_f32 v2, v2, v3
	v_cvt_pk_bf16_f32 v1, v8, v9
	v_cvt_pk_bf16_f32 v3, v10, v11
	v_permlane16_swap_b32_e32 v0, v2
	s_nop 0
	v_permlane16_swap_b32_e32 v1, v3
	global_store_dwordx4 v[4:5], v[0:3], off sc1
	v_pk_mul_f32 v[8:9], v[6:7], v[54:55] op_sel_hi:[0,1]
	v_pk_mul_f32 v[10:11], v[6:7], v[46:47] op_sel_hi:[0,1]
	v_pk_mul_f32 v[0:1], v[6:7], v[52:53] op_sel_hi:[0,1]
	v_pk_mul_f32 v[2:3], v[6:7], v[44:45] op_sel_hi:[0,1]
	v_cvt_pk_bf16_f32 v0, v0, v1
	v_cvt_pk_bf16_f32 v2, v2, v3
	v_cvt_pk_bf16_f32 v1, v8, v9
	v_cvt_pk_bf16_f32 v3, v10, v11
	v_permlane16_swap_b32_e32 v0, v2
	s_nop 0
	v_permlane16_swap_b32_e32 v1, v3
	global_store_dwordx4 v[4:5], v[0:3], off offset:64 sc1
	s_cbranch_scc1 .LBB0_318

.LBB0_325:
	v_add_u32_e32 v46, 0, v33
	ds_read_b128 v[34:37], v46
	ds_read_b128 v[38:41], v46 offset:64
	v_add_u32_e32 v47, 0, v32
	s_add_i32 s10, s10, -4
	v_add_u32_e32 v33, 0x4400, v33
	s_waitcnt vmcnt(3) lgkmcnt(1)
	v_mfma_f32_16x16x32_bf16 v[34:37], v[16:19], v[34:37], 0
	v_add_u32_e32 v32, 0x100, v32
	s_cmp_lg_u32 s10, 0
	s_waitcnt vmcnt(2) lgkmcnt(0)
	v_mfma_f32_16x16x32_bf16 v[34:37], v[20:23], v[38:41], v[34:37]
	ds_read_b128 v[38:41], v46 offset:128
	ds_read_b128 v[42:45], v46 offset:192
	s_waitcnt vmcnt(1) lgkmcnt(1)
	v_mfma_f32_16x16x32_bf16 v[34:37], v[24:27], v[38:41], v[34:37]
	v_add_u32_e32 v38, 0x11000, v47
	v_add_u32_e32 v39, 0x11400, v47
	s_waitcnt vmcnt(0) lgkmcnt(0)
	v_mfma_f32_16x16x32_bf16 v[34:37], v[28:31], v[42:45], v[34:37]
	s_nop 7
	v_pk_mul_f32 v[34:35], v[34:35], s[0:1] op_sel_hi:[1,0]
	v_pk_mul_f32 v[36:37], v[36:37], s[0:1] op_sel_hi:[1,0]
	v_cvt_pk_bf16_f32 v34, v34, v35
	v_cvt_pk_bf16_f32 v35, v36, v37
	ds_write_b32 v38, v34
	ds_write_b32 v39, v35
	ds_read_b128 v[34:37], v46 offset:4352
	ds_read_b128 v[38:41], v46 offset:4416
	s_waitcnt lgkmcnt(1)
	v_mfma_f32_16x16x32_bf16 v[34:37], v[16:19], v[34:37], 0
	s_waitcnt lgkmcnt(0)
	v_mfma_f32_16x16x32_bf16 v[34:37], v[20:23], v[38:41], v[34:37]
	ds_read_b128 v[38:41], v46 offset:4480
	ds_read_b128 v[42:45], v46 offset:4544
	s_waitcnt lgkmcnt(1)
	v_mfma_f32_16x16x32_bf16 v[34:37], v[24:27], v[38:41], v[34:37]
	v_add_u32_e32 v38, 0x11040, v47
	v_add_u32_e32 v39, 0x11440, v47
	s_waitcnt lgkmcnt(0)
	v_mfma_f32_16x16x32_bf16 v[34:37], v[28:31], v[42:45], v[34:37]
	s_nop 7
	v_pk_mul_f32 v[34:35], v[34:35], s[0:1] op_sel_hi:[1,0]
	v_pk_mul_f32 v[36:37], v[36:37], s[0:1] op_sel_hi:[1,0]
	v_cvt_pk_bf16_f32 v34, v34, v35
	v_cvt_pk_bf16_f32 v35, v36, v37
	ds_write_b32 v38, v34
	ds_write_b32 v39, v35
	ds_read_b128 v[34:37], v46 offset:8704
	ds_read_b128 v[38:41], v46 offset:8768
	s_waitcnt lgkmcnt(1)
	v_mfma_f32_16x16x32_bf16 v[34:37], v[16:19], v[34:37], 0
	s_waitcnt lgkmcnt(0)
	v_mfma_f32_16x16x32_bf16 v[34:37], v[20:23], v[38:41], v[34:37]
	ds_read_b128 v[38:41], v46 offset:8832
	ds_read_b128 v[42:45], v46 offset:8896
	s_waitcnt lgkmcnt(1)
	v_mfma_f32_16x16x32_bf16 v[34:37], v[24:27], v[38:41], v[34:37]
	v_add_u32_e32 v38, 0x11080, v47
	v_add_u32_e32 v39, 0x11480, v47
	s_waitcnt lgkmcnt(0)
	v_mfma_f32_16x16x32_bf16 v[34:37], v[28:31], v[42:45], v[34:37]
	s_nop 7
	v_pk_mul_f32 v[34:35], v[34:35], s[0:1] op_sel_hi:[1,0]
	v_pk_mul_f32 v[36:37], v[36:37], s[0:1] op_sel_hi:[1,0]
	v_cvt_pk_bf16_f32 v34, v34, v35
	v_cvt_pk_bf16_f32 v35, v36, v37
	ds_write_b32 v38, v34
	ds_write_b32 v39, v35
	ds_read_b128 v[34:37], v46 offset:13056
	ds_read_b128 v[38:41], v46 offset:13120
	s_waitcnt lgkmcnt(1)
	v_mfma_f32_16x16x32_bf16 v[34:37], v[16:19], v[34:37], 0
	s_waitcnt lgkmcnt(0)
	v_mfma_f32_16x16x32_bf16 v[34:37], v[20:23], v[38:41], v[34:37]
	ds_read_b128 v[38:41], v46 offset:13184
	ds_read_b128 v[42:45], v46 offset:13248
	s_waitcnt lgkmcnt(1)
	v_mfma_f32_16x16x32_bf16 v[34:37], v[24:27], v[38:41], v[34:37]
	v_add_u32_e32 v38, 0x110c0, v47
	v_add_u32_e32 v39, 0x114c0, v47
	s_waitcnt lgkmcnt(0)
	v_mfma_f32_16x16x32_bf16 v[34:37], v[28:31], v[42:45], v[34:37]
	s_nop 7
	v_pk_mul_f32 v[34:35], v[34:35], s[0:1] op_sel_hi:[1,0]
	v_pk_mul_f32 v[36:37], v[36:37], s[0:1] op_sel_hi:[1,0]
	v_cvt_pk_bf16_f32 v34, v34, v35
	v_cvt_pk_bf16_f32 v35, v36, v37
	ds_write_b32 v38, v34
	ds_write_b32 v39, v35
	s_cbranch_scc1 .LBB0_325
	s_mul_i32 s10, s7, s3
	s_add_i32 s12, s10, s34
	s_lshr_b32 s13, s12, 7
	s_and_b64 s[10:11], s[20:21], exec
	s_cselect_b32 s13, s36, s13
	s_lshl_b32 s10, s7, 5
	s_and_b32 s12, s12, 0x7f
	s_add_i32 s14, s6, s10
	s_and_b64 s[10:11], s[20:21], exec
	s_cselect_b32 s10, s14, s12
	s_lshl_b32 s11, s13, 7
	s_waitcnt lgkmcnt(0)
	s_barrier
	s_add_i32 s10, s11, s10
	v_add_u32_e32 v16, s8, v129
	s_ashr_i32 s11, s10, 31
	ds_read_b128 v[16:19], v16
	ds_read_b128 v[20:23], v159
	s_lshl_b64 s[10:11], s[10:11], 16
	s_add_u32 s10, s96, s10
	s_addc_u32 s11, s91, s11
	v_lshl_add_u64 v[24:25], s[10:11], 0, v[80:81]
	s_waitcnt lgkmcnt(1)
	global_store_dwordx4 v[24:25], v[16:19], off sc1
	ds_read_b128 v[16:19], v160
	v_lshl_add_u64 v[24:25], s[10:11], 0, v[82:83]
	s_waitcnt lgkmcnt(1)
	global_store_dwordx4 v[24:25], v[20:23], off sc1
	ds_read_b128 v[20:23], v161
	v_lshl_add_u64 v[24:25], s[10:11], 0, v[84:85]
	s_waitcnt lgkmcnt(1)
	global_store_dwordx4 v[24:25], v[16:19], off sc1
	ds_read_b128 v[16:19], v162
	v_lshl_add_u64 v[24:25], s[10:11], 0, v[86:87]
	s_waitcnt lgkmcnt(1)
	global_store_dwordx4 v[24:25], v[20:23], off sc1
	v_lshl_add_u64 v[24:25], s[10:11], 0, v[120:121]
	ds_read_b128 v[20:23], v163
	s_waitcnt lgkmcnt(1)
	global_store_dwordx4 v[24:25], v[16:19], off sc1
	ds_read_b128 v[16:19], v164
	ds_read_b128 v[24:27], v165
	v_lshl_add_u64 v[28:29], s[10:11], 0, v[122:123]
	s_waitcnt lgkmcnt(2)
	global_store_dwordx4 v[28:29], v[20:23], off sc1
	s_add_i32 s7, s7, 1
	s_and_b64 vcc, exec, s[4:5]
	v_lshl_add_u64 v[20:21], s[10:11], 0, v[124:125]
	s_waitcnt lgkmcnt(1)
	global_store_dwordx4 v[20:21], v[16:19], off sc1
	s_nop 1
	v_lshl_add_u64 v[16:17], s[10:11], 0, v[126:127]
	s_waitcnt lgkmcnt(0)
	global_store_dwordx4 v[16:17], v[24:27], off sc1
	s_cbranch_vccz .LBB0_320
